# M2: ff1 epilogue - write-back (plain) stores for units followed by another unit, write-through sc1 only for the WG's final unit; on top of P1
# speedup vs baseline: 1.0161x; 1.0161x over previous
.LBB0_237:
	s_lshl_b32 s6, s78, 8
	v_mbcnt_lo_u32_b32 v141, -1, 0
	v_mbcnt_hi_u32_b32 v141, -1, v141
	s_add_i32 s6, s6, s71
	v_and_or_b32 v140, v141, 15, s6
	s_lshl_b32 s6, s77, 8
	v_ashrrev_i32_e32 v141, 1, v141
	s_or_b32 s6, s6, s81
	v_and_b32_e32 v141, -8, v141
	v_add_u32_e32 v142, s6, v141
	v_ashrrev_i32_e32 v141, 31, v140
	v_lshlrev_b64 v[144:145], 13, v[140:141]
	v_ashrrev_i32_e32 v143, 31, v142
	v_lshl_add_u64 v[144:145], s[4:5], 0, v[144:145]
	s_movk_i32 s6, 0x1000
	v_lshl_add_u64 v[144:145], v[142:143], 1, v[144:145]
	v_cmp_gt_i32_e32 vcc, s6, v142
	s_and_saveexec_b64 s[6:7], vcc
	s_cbranch_execz .LBB0_239
	v_max_f32_e32 v122, 0, v122
	v_max_f32_e32 v123, 0, v123
	v_max_f32_e32 v124, 0, v124
	v_max_f32_e32 v125, 0, v125
	v_max_f32_e32 v126, 0, v126
	v_max_f32_e32 v127, 0, v127
	v_max_f32_e32 v128, 0, v128
	v_max_f32_e32 v129, 0, v129
	v_pk_mul_f32 v[122:123], v[122:123], v[122:123]
	v_pk_mul_f32 v[124:125], v[124:125], v[124:125]
	v_pk_mul_f32 v[126:127], v[126:127], v[126:127]
	v_pk_mul_f32 v[128:129], v[128:129], v[128:129]
	v_cvt_pk_bf16_f32 v125, v124, v125
	v_cvt_pk_bf16_f32 v124, v122, v123
	v_cvt_pk_bf16_f32 v122, v126, v127
	v_cvt_pk_bf16_f32 v123, v128, v129
	s_cmp_lg_u64 s[36:37], 0
	s_cbranch_scc1 .Lm2_wb1
	flat_store_dwordx4 v[144:145], v[122:125] sc1
	s_branch .Lm2_j1
.Lm2_wb1:
	flat_store_dwordx4 v[144:145], v[122:125]
.Lm2_j1:
.LBB0_239:
	s_or_b64 exec, exec, s[6:7]
	v_cmp_gt_i32_e64 s[38:39], s24, v142
	s_and_saveexec_b64 s[6:7], s[38:39]
	s_cbranch_execz .LBB0_241
	v_max_f32_e32 v114, 0, v114
	v_max_f32_e32 v115, 0, v115
	v_max_f32_e32 v116, 0, v116
	v_max_f32_e32 v117, 0, v117
	v_max_f32_e32 v118, 0, v118
	v_max_f32_e32 v119, 0, v119
	v_max_f32_e32 v120, 0, v120
	v_max_f32_e32 v121, 0, v121
	v_pk_mul_f32 v[114:115], v[114:115], v[114:115]
	v_pk_mul_f32 v[116:117], v[116:117], v[116:117]
	v_pk_mul_f32 v[118:119], v[118:119], v[118:119]
	v_pk_mul_f32 v[120:121], v[120:121], v[120:121]
	v_cvt_pk_bf16_f32 v117, v116, v117
	v_cvt_pk_bf16_f32 v116, v114, v115
	v_cvt_pk_bf16_f32 v114, v118, v119
	v_cvt_pk_bf16_f32 v115, v120, v121
	s_cmp_lg_u64 s[36:37], 0
	s_cbranch_scc1 .Lm2_wb2
	flat_store_dwordx4 v[144:145], v[114:117] offset:256 sc1
	s_branch .Lm2_j2
.Lm2_wb2:
	flat_store_dwordx4 v[144:145], v[114:117] offset:256
.Lm2_j2:
.LBB0_241:
	s_or_b64 exec, exec, s[6:7]
	s_nop 0
	v_or_b32_e32 v114, 16, v140
	v_ashrrev_i32_e32 v115, 31, v114
	v_lshlrev_b64 v[114:115], 13, v[114:115]
	v_lshl_add_u64 v[114:115], s[4:5], 0, v[114:115]
	v_lshl_add_u64 v[114:115], v[142:143], 1, v[114:115]
	s_and_saveexec_b64 s[6:7], vcc
	s_cbranch_execz .LBB0_243
	v_max_f32_e32 v106, 0, v106
	v_max_f32_e32 v107, 0, v107
	v_max_f32_e32 v108, 0, v108
	v_max_f32_e32 v109, 0, v109
	v_max_f32_e32 v110, 0, v110
	v_max_f32_e32 v111, 0, v111
	v_max_f32_e32 v112, 0, v112
	v_max_f32_e32 v113, 0, v113
	v_pk_mul_f32 v[106:107], v[106:107], v[106:107]
	v_pk_mul_f32 v[108:109], v[108:109], v[108:109]
	v_pk_mul_f32 v[110:111], v[110:111], v[110:111]
	v_pk_mul_f32 v[112:113], v[112:113], v[112:113]
	v_cvt_pk_bf16_f32 v109, v108, v109
	v_cvt_pk_bf16_f32 v108, v106, v107
	v_cvt_pk_bf16_f32 v106, v110, v111
	v_cvt_pk_bf16_f32 v107, v112, v113
	s_cmp_lg_u64 s[36:37], 0
	s_cbranch_scc1 .Lm2_wb3
	flat_store_dwordx4 v[114:115], v[106:109] sc1
	s_branch .Lm2_j3
.Lm2_wb3:
	flat_store_dwordx4 v[114:115], v[106:109]
.Lm2_j3:
.LBB0_243:
	s_or_b64 exec, exec, s[6:7]
	s_and_saveexec_b64 s[6:7], s[38:39]
	s_cbranch_execz .LBB0_245
	v_max_f32_e32 v98, 0, v98
	v_max_f32_e32 v99, 0, v99
	v_max_f32_e32 v100, 0, v100
	v_max_f32_e32 v101, 0, v101
	v_max_f32_e32 v102, 0, v102
	v_max_f32_e32 v103, 0, v103
	v_max_f32_e32 v104, 0, v104
	v_max_f32_e32 v105, 0, v105
	v_pk_mul_f32 v[98:99], v[98:99], v[98:99]
	v_pk_mul_f32 v[100:101], v[100:101], v[100:101]
	v_pk_mul_f32 v[102:103], v[102:103], v[102:103]
	v_pk_mul_f32 v[104:105], v[104:105], v[104:105]
	v_cvt_pk_bf16_f32 v101, v100, v101
	v_cvt_pk_bf16_f32 v100, v98, v99
	v_cvt_pk_bf16_f32 v98, v102, v103
	v_cvt_pk_bf16_f32 v99, v104, v105
	s_cmp_lg_u64 s[36:37], 0
	s_cbranch_scc1 .Lm2_wb4
	flat_store_dwordx4 v[114:115], v[98:101] offset:256 sc1
	s_branch .Lm2_j4
.Lm2_wb4:
	flat_store_dwordx4 v[114:115], v[98:101] offset:256
.Lm2_j4:
.LBB0_245:
	s_or_b64 exec, exec, s[6:7]
	s_nop 0
	v_or_b32_e32 v98, 32, v140
	v_ashrrev_i32_e32 v99, 31, v98
	v_lshlrev_b64 v[98:99], 13, v[98:99]
	v_lshl_add_u64 v[98:99], s[4:5], 0, v[98:99]
	v_lshl_add_u64 v[98:99], v[142:143], 1, v[98:99]
	s_and_saveexec_b64 s[6:7], vcc
	s_cbranch_execz .LBB0_247
	v_max_f32_e32 v90, 0, v90
	v_max_f32_e32 v91, 0, v91
	v_max_f32_e32 v92, 0, v92
	v_max_f32_e32 v93, 0, v93
	v_max_f32_e32 v94, 0, v94
	v_max_f32_e32 v95, 0, v95
	v_max_f32_e32 v96, 0, v96
	v_max_f32_e32 v97, 0, v97
	v_pk_mul_f32 v[90:91], v[90:91], v[90:91]
	v_pk_mul_f32 v[92:93], v[92:93], v[92:93]
	v_pk_mul_f32 v[94:95], v[94:95], v[94:95]
	v_pk_mul_f32 v[96:97], v[96:97], v[96:97]
	v_cvt_pk_bf16_f32 v93, v92, v93
	v_cvt_pk_bf16_f32 v92, v90, v91
	v_cvt_pk_bf16_f32 v90, v94, v95
	v_cvt_pk_bf16_f32 v91, v96, v97
	s_cmp_lg_u64 s[36:37], 0
	s_cbranch_scc1 .Lm2_wb5
	flat_store_dwordx4 v[98:99], v[90:93] sc1
	s_branch .Lm2_j5
.Lm2_wb5:
	flat_store_dwordx4 v[98:99], v[90:93]
.Lm2_j5:
.LBB0_247:
	s_or_b64 exec, exec, s[6:7]
	s_and_saveexec_b64 s[6:7], s[38:39]
	s_cbranch_execz .LBB0_249
	v_max_f32_e32 v82, 0, v82
	v_max_f32_e32 v83, 0, v83
	v_max_f32_e32 v84, 0, v84
	v_max_f32_e32 v85, 0, v85
	v_max_f32_e32 v86, 0, v86
	v_max_f32_e32 v87, 0, v87
	v_max_f32_e32 v88, 0, v88
	v_max_f32_e32 v89, 0, v89
	v_pk_mul_f32 v[82:83], v[82:83], v[82:83]
	v_pk_mul_f32 v[84:85], v[84:85], v[84:85]
	v_pk_mul_f32 v[86:87], v[86:87], v[86:87]
	v_pk_mul_f32 v[88:89], v[88:89], v[88:89]
	v_cvt_pk_bf16_f32 v85, v84, v85
	v_cvt_pk_bf16_f32 v84, v82, v83
	v_cvt_pk_bf16_f32 v82, v86, v87
	v_cvt_pk_bf16_f32 v83, v88, v89
	s_cmp_lg_u64 s[36:37], 0
	s_cbranch_scc1 .Lm2_wb6
	flat_store_dwordx4 v[98:99], v[82:85] offset:256 sc1
	s_branch .Lm2_j6
.Lm2_wb6:
	flat_store_dwordx4 v[98:99], v[82:85] offset:256
.Lm2_j6:
.LBB0_249:
	s_or_b64 exec, exec, s[6:7]
	s_nop 0
	v_or_b32_e32 v82, 48, v140
	v_ashrrev_i32_e32 v83, 31, v82
	v_lshlrev_b64 v[82:83], 13, v[82:83]
	v_lshl_add_u64 v[82:83], s[4:5], 0, v[82:83]
	v_lshl_add_u64 v[82:83], v[142:143], 1, v[82:83]
	s_and_saveexec_b64 s[6:7], vcc
	s_cbranch_execz .LBB0_251
	v_max_f32_e32 v72, 0, v72
	v_max_f32_e32 v73, 0, v73
	v_max_f32_e32 v74, 0, v74
	v_max_f32_e32 v75, 0, v75
	v_max_f32_e32 v76, 0, v76
	v_max_f32_e32 v77, 0, v77
	v_max_f32_e32 v78, 0, v78
	v_max_f32_e32 v79, 0, v79
	v_pk_mul_f32 v[72:73], v[72:73], v[72:73]
	v_pk_mul_f32 v[74:75], v[74:75], v[74:75]
	v_pk_mul_f32 v[76:77], v[76:77], v[76:77]
	v_pk_mul_f32 v[78:79], v[78:79], v[78:79]
	v_cvt_pk_bf16_f32 v75, v74, v75
	v_cvt_pk_bf16_f32 v74, v72, v73
	v_cvt_pk_bf16_f32 v72, v76, v77
	v_cvt_pk_bf16_f32 v73, v78, v79
	s_cmp_lg_u64 s[36:37], 0
	s_cbranch_scc1 .Lm2_wb7
	flat_store_dwordx4 v[82:83], v[72:75] sc1
	s_branch .Lm2_j7
.Lm2_wb7:
	flat_store_dwordx4 v[82:83], v[72:75]
.Lm2_j7:
.LBB0_251:
	s_or_b64 exec, exec, s[6:7]
	s_and_saveexec_b64 s[6:7], s[38:39]
	s_cbranch_execz .LBB0_253
	v_max_f32_e32 v64, 0, v64
	v_max_f32_e32 v65, 0, v65
	v_max_f32_e32 v66, 0, v66
	v_max_f32_e32 v67, 0, v67
	v_max_f32_e32 v68, 0, v68
	v_max_f32_e32 v69, 0, v69
	v_max_f32_e32 v70, 0, v70
	v_max_f32_e32 v71, 0, v71
	v_pk_mul_f32 v[64:65], v[64:65], v[64:65]
	v_pk_mul_f32 v[66:67], v[66:67], v[66:67]
	v_pk_mul_f32 v[68:69], v[68:69], v[68:69]
	v_pk_mul_f32 v[70:71], v[70:71], v[70:71]
	v_cvt_pk_bf16_f32 v67, v66, v67
	v_cvt_pk_bf16_f32 v66, v64, v65
	v_cvt_pk_bf16_f32 v64, v68, v69
	v_cvt_pk_bf16_f32 v65, v70, v71
	s_cmp_lg_u64 s[36:37], 0
	s_cbranch_scc1 .Lm2_wb8
	flat_store_dwordx4 v[82:83], v[64:67] offset:256 sc1
	s_branch .Lm2_j8
.Lm2_wb8:
	flat_store_dwordx4 v[82:83], v[64:67] offset:256
.Lm2_j8:
.LBB0_253:
	s_or_b64 exec, exec, s[6:7]
	s_nop 0
	v_lshlrev_b64 v[64:65], 13, v[140:141]
	v_lshl_add_u64 v[64:65], s[4:5], 0, v[64:65]
	v_lshl_add_u64 v[64:65], v[142:143], 1, v[64:65]
	s_mov_b64 s[6:7], 0x100000
	v_lshl_add_u64 v[64:65], v[64:65], 0, s[6:7]
	s_and_saveexec_b64 s[6:7], vcc
	s_cbranch_execz .LBB0_255
	v_max_f32_e32 v56, 0, v56
	v_max_f32_e32 v57, 0, v57
	v_max_f32_e32 v58, 0, v58
	v_max_f32_e32 v59, 0, v59
	v_max_f32_e32 v60, 0, v60
	v_max_f32_e32 v61, 0, v61
	v_max_f32_e32 v62, 0, v62
	v_max_f32_e32 v63, 0, v63
	v_pk_mul_f32 v[56:57], v[56:57], v[56:57]
	v_pk_mul_f32 v[58:59], v[58:59], v[58:59]
	v_pk_mul_f32 v[60:61], v[60:61], v[60:61]
	v_pk_mul_f32 v[62:63], v[62:63], v[62:63]
	v_cvt_pk_bf16_f32 v59, v58, v59
	v_cvt_pk_bf16_f32 v58, v56, v57
	v_cvt_pk_bf16_f32 v56, v60, v61
	v_cvt_pk_bf16_f32 v57, v62, v63
	s_cmp_lg_u64 s[36:37], 0
	s_cbranch_scc1 .Lm2_wb9
	flat_store_dwordx4 v[64:65], v[56:59] sc1
	s_branch .Lm2_j9
.Lm2_wb9:
	flat_store_dwordx4 v[64:65], v[56:59]
.Lm2_j9:
.LBB0_255:
	s_or_b64 exec, exec, s[6:7]
	s_and_saveexec_b64 s[6:7], s[38:39]
	s_cbranch_execz .LBB0_257
	v_max_f32_e32 v48, 0, v48
	v_max_f32_e32 v49, 0, v49
	v_max_f32_e32 v50, 0, v50
	v_max_f32_e32 v51, 0, v51
	v_max_f32_e32 v52, 0, v52
	v_max_f32_e32 v53, 0, v53
	v_max_f32_e32 v54, 0, v54
	v_max_f32_e32 v55, 0, v55
	v_pk_mul_f32 v[48:49], v[48:49], v[48:49]
	v_pk_mul_f32 v[50:51], v[50:51], v[50:51]
	v_pk_mul_f32 v[52:53], v[52:53], v[52:53]
	v_pk_mul_f32 v[54:55], v[54:55], v[54:55]
	v_cvt_pk_bf16_f32 v51, v50, v51
	v_cvt_pk_bf16_f32 v50, v48, v49
	v_cvt_pk_bf16_f32 v48, v52, v53
	v_cvt_pk_bf16_f32 v49, v54, v55
	s_cmp_lg_u64 s[36:37], 0
	s_cbranch_scc1 .Lm2_wb10
	flat_store_dwordx4 v[64:65], v[48:51] offset:256 sc1
	s_branch .Lm2_j10
.Lm2_wb10:
	flat_store_dwordx4 v[64:65], v[48:51] offset:256
.Lm2_j10:
.LBB0_257:
	s_or_b64 exec, exec, s[6:7]
	s_nop 0
	v_lshlrev_b64 v[48:49], 13, v[140:141]
	v_lshl_add_u64 v[48:49], s[4:5], 0, v[48:49]
	v_lshl_add_u64 v[48:49], v[142:143], 1, v[48:49]
	s_mov_b64 s[6:7], 0x120000
	v_lshl_add_u64 v[48:49], v[48:49], 0, s[6:7]
	s_and_saveexec_b64 s[6:7], vcc
	s_cbranch_execz .LBB0_259
	v_max_f32_e32 v40, 0, v40
	v_max_f32_e32 v41, 0, v41
	v_max_f32_e32 v42, 0, v42
	v_max_f32_e32 v43, 0, v43
	v_max_f32_e32 v44, 0, v44
	v_max_f32_e32 v45, 0, v45
	v_max_f32_e32 v46, 0, v46
	v_max_f32_e32 v47, 0, v47
	v_pk_mul_f32 v[40:41], v[40:41], v[40:41]
	v_pk_mul_f32 v[42:43], v[42:43], v[42:43]
	v_pk_mul_f32 v[44:45], v[44:45], v[44:45]
	v_pk_mul_f32 v[46:47], v[46:47], v[46:47]
	v_cvt_pk_bf16_f32 v43, v42, v43
	v_cvt_pk_bf16_f32 v42, v40, v41
	v_cvt_pk_bf16_f32 v40, v44, v45
	v_cvt_pk_bf16_f32 v41, v46, v47
	s_cmp_lg_u64 s[36:37], 0
	s_cbranch_scc1 .Lm2_wb11
	flat_store_dwordx4 v[48:49], v[40:43] sc1
	s_branch .Lm2_j11
.Lm2_wb11:
	flat_store_dwordx4 v[48:49], v[40:43]
.Lm2_j11:
.LBB0_259:
	s_or_b64 exec, exec, s[6:7]
	s_and_saveexec_b64 s[6:7], s[38:39]
	s_cbranch_execz .LBB0_261
	v_max_f32_e32 v32, 0, v32
	v_max_f32_e32 v33, 0, v33
	v_max_f32_e32 v34, 0, v34
	v_max_f32_e32 v35, 0, v35
	v_max_f32_e32 v36, 0, v36
	v_max_f32_e32 v37, 0, v37
	v_max_f32_e32 v38, 0, v38
	v_max_f32_e32 v39, 0, v39
	v_pk_mul_f32 v[32:33], v[32:33], v[32:33]
	v_pk_mul_f32 v[34:35], v[34:35], v[34:35]
	v_pk_mul_f32 v[36:37], v[36:37], v[36:37]
	v_pk_mul_f32 v[38:39], v[38:39], v[38:39]
	v_cvt_pk_bf16_f32 v35, v34, v35
	v_cvt_pk_bf16_f32 v34, v32, v33
	v_cvt_pk_bf16_f32 v32, v36, v37
	v_cvt_pk_bf16_f32 v33, v38, v39
	s_cmp_lg_u64 s[36:37], 0
	s_cbranch_scc1 .Lm2_wb12
	flat_store_dwordx4 v[48:49], v[32:35] offset:256 sc1
	s_branch .Lm2_j12
.Lm2_wb12:
	flat_store_dwordx4 v[48:49], v[32:35] offset:256
.Lm2_j12:
.LBB0_261:
	s_or_b64 exec, exec, s[6:7]
	s_nop 0
	v_lshlrev_b64 v[32:33], 13, v[140:141]
	v_lshl_add_u64 v[32:33], s[4:5], 0, v[32:33]
	v_lshl_add_u64 v[32:33], v[142:143], 1, v[32:33]
	s_mov_b64 s[6:7], 0x140000
	v_lshl_add_u64 v[32:33], v[32:33], 0, s[6:7]
	s_and_saveexec_b64 s[6:7], vcc
	s_cbranch_execz .LBB0_263
	v_max_f32_e32 v24, 0, v24
	v_max_f32_e32 v25, 0, v25
	v_max_f32_e32 v26, 0, v26
	v_max_f32_e32 v27, 0, v27
	v_max_f32_e32 v28, 0, v28
	v_max_f32_e32 v29, 0, v29
	v_max_f32_e32 v30, 0, v30
	v_max_f32_e32 v31, 0, v31
	v_pk_mul_f32 v[24:25], v[24:25], v[24:25]
	v_pk_mul_f32 v[26:27], v[26:27], v[26:27]
	v_pk_mul_f32 v[28:29], v[28:29], v[28:29]
	v_pk_mul_f32 v[30:31], v[30:31], v[30:31]
	v_cvt_pk_bf16_f32 v27, v26, v27
	v_cvt_pk_bf16_f32 v26, v24, v25
	v_cvt_pk_bf16_f32 v24, v28, v29
	v_cvt_pk_bf16_f32 v25, v30, v31
	s_cmp_lg_u64 s[36:37], 0
	s_cbranch_scc1 .Lm2_wb13
	flat_store_dwordx4 v[32:33], v[24:27] sc1
	s_branch .Lm2_j13
.Lm2_wb13:
	flat_store_dwordx4 v[32:33], v[24:27]
.Lm2_j13:
.LBB0_263:
	s_or_b64 exec, exec, s[6:7]
	s_and_saveexec_b64 s[6:7], s[38:39]
	s_cbranch_execz .LBB0_265
	v_max_f32_e32 v16, 0, v16
	v_max_f32_e32 v17, 0, v17
	v_max_f32_e32 v18, 0, v18
	v_max_f32_e32 v19, 0, v19
	v_max_f32_e32 v20, 0, v20
	v_max_f32_e32 v21, 0, v21
	v_max_f32_e32 v22, 0, v22
	v_max_f32_e32 v23, 0, v23
	v_pk_mul_f32 v[16:17], v[16:17], v[16:17]
	v_pk_mul_f32 v[18:19], v[18:19], v[18:19]
	v_pk_mul_f32 v[20:21], v[20:21], v[20:21]
	v_pk_mul_f32 v[22:23], v[22:23], v[22:23]
	v_cvt_pk_bf16_f32 v19, v18, v19
	v_cvt_pk_bf16_f32 v18, v16, v17
	v_cvt_pk_bf16_f32 v16, v20, v21
	v_cvt_pk_bf16_f32 v17, v22, v23
	s_cmp_lg_u64 s[36:37], 0
	s_cbranch_scc1 .Lm2_wb14
	flat_store_dwordx4 v[32:33], v[16:19] offset:256 sc1
	s_branch .Lm2_j14
.Lm2_wb14:
	flat_store_dwordx4 v[32:33], v[16:19] offset:256
.Lm2_j14:
.LBB0_265:
	s_or_b64 exec, exec, s[6:7]
	s_nop 0
	v_lshlrev_b64 v[16:17], 13, v[140:141]
	v_lshl_add_u64 v[16:17], s[4:5], 0, v[16:17]
	v_lshl_add_u64 v[16:17], v[142:143], 1, v[16:17]
	s_mov_b64 s[6:7], 0x160000
	v_lshl_add_u64 v[16:17], v[16:17], 0, s[6:7]
	s_and_saveexec_b64 s[6:7], vcc
	s_cbranch_execnz .LBB0_268
	s_or_b64 exec, exec, s[6:7]
	s_and_saveexec_b64 s[6:7], s[38:39]
	s_cbranch_execnz .LBB0_269

.LBB0_268:
	v_max_f32_e32 v8, 0, v8
	v_max_f32_e32 v9, 0, v9
	v_max_f32_e32 v10, 0, v10
	v_max_f32_e32 v11, 0, v11
	v_max_f32_e32 v12, 0, v12
	v_max_f32_e32 v13, 0, v13
	v_max_f32_e32 v14, 0, v14
	v_max_f32_e32 v15, 0, v15
	v_pk_mul_f32 v[8:9], v[8:9], v[8:9]
	v_pk_mul_f32 v[10:11], v[10:11], v[10:11]
	v_pk_mul_f32 v[12:13], v[12:13], v[12:13]
	v_pk_mul_f32 v[14:15], v[14:15], v[14:15]
	v_cvt_pk_bf16_f32 v11, v10, v11
	v_cvt_pk_bf16_f32 v10, v8, v9
	v_cvt_pk_bf16_f32 v8, v12, v13
	v_cvt_pk_bf16_f32 v9, v14, v15
	s_cmp_lg_u64 s[36:37], 0
	s_cbranch_scc1 .Lm2_wb15
	flat_store_dwordx4 v[16:17], v[8:11] sc1
	s_branch .Lm2_j15
.Lm2_wb15:
	flat_store_dwordx4 v[16:17], v[8:11]

.LBB0_269:
	v_max_f32_e32 v0, 0, v0
	v_max_f32_e32 v1, 0, v1
	v_max_f32_e32 v2, 0, v2
	v_max_f32_e32 v3, 0, v3
	v_max_f32_e32 v4, 0, v4
	v_max_f32_e32 v5, 0, v5
	v_max_f32_e32 v6, 0, v6
	v_max_f32_e32 v7, 0, v7
	v_pk_mul_f32 v[0:1], v[0:1], v[0:1]
	v_pk_mul_f32 v[2:3], v[2:3], v[2:3]
	v_pk_mul_f32 v[4:5], v[4:5], v[4:5]
	v_pk_mul_f32 v[6:7], v[6:7], v[6:7]
	v_cvt_pk_bf16_f32 v3, v2, v3
	v_cvt_pk_bf16_f32 v2, v0, v1
	v_cvt_pk_bf16_f32 v0, v4, v5
	v_cvt_pk_bf16_f32 v1, v6, v7
	s_cmp_lg_u64 s[36:37], 0
	s_cbranch_scc1 .Lm2_wb16
	flat_store_dwordx4 v[16:17], v[0:3] offset:256 sc1
	s_branch .Lm2_j16
.Lm2_wb16:
	flat_store_dwordx4 v[16:17], v[0:3] offset:256
.Lm2_j16:
	s_or_b64 exec, exec, s[6:7]
	s_andn2_b64 vcc, exec, s[36:37]
	s_mov_b64 s[6:7], -1
	s_cbranch_vccnz .LBB0_230
.LBB0_270:
	s_andn2_b64 vcc, exec, s[0:1]
	s_cbranch_vccnz .LBB0_229
	s_barrier
	s_branch .LBB0_229
